# NSA selected-branch loop: next iteration's selection-bit test computed before the loop-back barrier (loop-edge rotation)
# baseline (speedup 1.0000x reference)
.LBB0_740:
	s_or_b64 exec, exec, s[6:7]
	v_readlane_b32 s6, v248, 12
	s_waitcnt lgkmcnt(0)
	s_barrier
	s_mov_b32 s79, s95
	v_mov_b32_e32 v0, s6
	ds_read_b32 v2, v0
	v_mov_b32_e32 v0, 0
	v_mov_b32_e32 v4, 0
	v_mov_b32_e32 v8, 0
	v_mov_b32_e32 v12, 0
	s_waitcnt lgkmcnt(0)
	v_readfirstlane_b32 s94, v2
	v_bfe_u32 v2, v101, 1, 1
	s_cmp_lt_i32 s94, 1
	v_or_b32_e32 v195, v99, v2
	v_bitop3_b32 v197, v99, v193, v2 bitop3:0x36
	v_bitop3_b32 v196, v99, v194, v2 bitop3:0x36
	v_mov_b32_e32 v80, 0
	v_mov_b32_e32 v84, 0
	v_mov_b32_e32 v88, 0
	v_mov_b32_e32 v92, 0
	v_mov_b32_e32 v96, 0
	v_mov_b32_e32 v100, 0
	v_mov_b32_e32 v105, 0
	v_mov_b32_e32 v109, 0
	v_mov_b32_e32 v208, 0
	v_mov_b32_e32 v212, 0
	v_mov_b32_e32 v216, 0
	v_mov_b32_e32 v220, 0
	v_mov_b32_e32 v2, 0
	v_mov_b32_e32 v6, 0
	v_mov_b32_e32 v10, 0
	v_mov_b32_e32 v14, 0
	v_mov_b32_e32 v82, 0
	v_mov_b32_e32 v86, 0
	v_mov_b32_e32 v90, 0
	v_mov_b32_e32 v94, 0
	v_mov_b32_e32 v98, 0
	v_mov_b32_e32 v103, 0
	v_mov_b32_e32 v107, 0
	v_mov_b32_e32 v111, 0
	v_mov_b32_e32 v210, 0
	v_mov_b32_e32 v214, 0
	v_mov_b32_e32 v218, 0
	v_mov_b32_e32 v222, 0
	v_mov_b32_e32 v3, 0
	v_mov_b32_e32 v7, 0
	v_mov_b32_e32 v11, 0
	v_mov_b32_e32 v15, 0
	v_mov_b32_e32 v83, 0
	v_mov_b32_e32 v87, 0
	v_mov_b32_e32 v91, 0
	v_mov_b32_e32 v95, 0
	v_mov_b32_e32 v99, 0
	v_mov_b32_e32 v104, 0
	v_mov_b32_e32 v108, 0
	v_mov_b32_e32 v207, 0
	v_mov_b32_e32 v211, 0
	v_mov_b32_e32 v215, 0
	v_mov_b32_e32 v219, 0
	v_mov_b32_e32 v223, 0
	v_mov_b32_e32 v5, 0
	v_mov_b32_e32 v9, 0
	v_mov_b32_e32 v13, 0
	v_mov_b32_e32 v81, 0
	v_mov_b32_e32 v85, 0
	v_mov_b32_e32 v89, 0
	v_mov_b32_e32 v93, 0
	v_mov_b32_e32 v97, 0
	v_mov_b32_e32 v102, 0
	v_mov_b32_e32 v106, 0
	v_mov_b32_e32 v110, 0
	v_mov_b32_e32 v209, 0
	v_mov_b32_e32 v213, 0
	v_mov_b32_e32 v217, 0
	v_mov_b32_e32 v221, 0
	v_mov_b32_e32 v224, 0
	v_mov_b32_e32 v198, 0
	s_cbranch_scc1 .LBB0_752
	v_readlane_b32 s6, v248, 40
	v_readlane_b32 s7, v248, 41
	s_lshl_b64 s[6:7], s[6:7], 1
	s_add_u32 s8, s2, s6
	s_addc_u32 s9, s3, s7
	s_add_u32 s6, s8, 0x1b000000
	s_addc_u32 s7, s9, 0
	s_add_u32 s8, s8, 0x1a000000
	s_addc_u32 s9, s9, 0
	s_add_i32 s10, 0, 0x18820
	v_mov_b32_e32 v0, s10
	ds_read_b32 v2, v0
	v_and_b32_e32 v0, 28, v101
	s_mov_b32 m0, s0
	v_lshl_add_u32 v0, v0, 2, s44
	s_mov_b64 s[10:11], 0x2000
	s_waitcnt lgkmcnt(0)
	v_ashrrev_i32_e32 v3, 31, v2
	v_lshlrev_b64 v[2:3], 14, v[2:3]
	v_lshl_add_u64 v[4:5], s[8:9], 0, v[2:3]
	v_lshl_add_u64 v[4:5], v[4:5], 0, v[156:157]
	ds_read_b128 v[144:147], v0
	global_load_lds_dwordx4 v[4:5], off
	v_lshl_add_u64 v[4:5], v[4:5], 0, s[10:11]
	s_mov_b32 m0, s80
	v_lshl_add_u64 v[2:3], s[6:7], 0, v[2:3]
	global_load_lds_dwordx4 v[4:5], off
	v_lshl_add_u64 v[2:3], v[2:3], 0, v[156:157]
	s_mov_b32 m0, s81
	v_or_b32_e32 v0, s84, v187
	global_load_lds_dwordx4 v[2:3], off
	v_lshl_add_u64 v[2:3], v[2:3], 0, s[10:11]
	s_mov_b32 m0, s85
	v_lshl_add_u64 v[158:159], s[8:9], 0, v[156:157]
	global_load_lds_dwordx4 v[2:3], off
	v_or_b32_e32 v2, 32, v0
	v_cmp_gt_i32_e64 s[8:9], v2, v152
	v_or_b32_e32 v2, 33, v0
	v_cmp_gt_i32_e64 s[12:13], v2, v152
	v_or_b32_e32 v2, 2, v0
	v_or_b32_e32 v3, 34, v0
	v_cmp_gt_i32_e64 s[14:15], v2, v152
	v_or_b32_e32 v2, 3, v0
	v_cmp_gt_i32_e64 s[16:17], v3, v152
	v_or_b32_e32 v3, 35, v0
	v_cmp_gt_i32_e64 s[18:19], v2, v152
	v_or_b32_e32 v2, 8, v0
	v_cmp_gt_i32_e64 s[20:21], v3, v152
	v_or_b32_e32 v3, 40, v0
	v_cmp_gt_i32_e64 s[22:23], v2, v152
	v_or_b32_e32 v2, 9, v0
	v_cmp_gt_i32_e64 s[24:25], v3, v152
	v_or_b32_e32 v3, 41, v0
	v_cmp_gt_i32_e64 s[26:27], v2, v152
	v_or_b32_e32 v2, 10, v0
	v_cmp_gt_i32_e64 s[28:29], v3, v152
	v_or_b32_e32 v3, 42, v0
	v_cmp_gt_i32_e64 s[30:31], v2, v152
	v_or_b32_e32 v2, 11, v0
	v_cmp_gt_i32_e64 s[34:35], v3, v152
	v_or_b32_e32 v3, 43, v0
	v_cmp_gt_i32_e64 s[36:37], v2, v152
	v_or_b32_e32 v2, 16, v0
	v_cmp_gt_i32_e64 s[38:39], v3, v152
	v_or_b32_e32 v3, 48, v0
	v_cmp_gt_i32_e64 s[40:41], v2, v152
	v_or_b32_e32 v2, 17, v0
	v_cmp_gt_i32_e64 s[42:43], v3, v152
	v_or_b32_e32 v3, 49, v0
	v_cmp_gt_i32_e64 s[44:45], v2, v152
	v_or_b32_e32 v2, 18, v0
	v_cmp_gt_i32_e64 s[46:47], v3, v152
	v_or_b32_e32 v3, 50, v0
	v_cmp_gt_i32_e64 s[48:49], v2, v152
	v_or_b32_e32 v2, 19, v0
	v_cmp_gt_i32_e64 s[50:51], v3, v152
	v_or_b32_e32 v3, 51, v0
	v_cmp_gt_i32_e64 s[52:53], v2, v152
	v_or_b32_e32 v2, 24, v0
	v_cmp_gt_i32_e64 s[54:55], v3, v152
	v_or_b32_e32 v3, 56, v0
	v_cmp_gt_i32_e64 s[56:57], v2, v152
	v_or_b32_e32 v2, 25, v0
	v_cmp_gt_i32_e64 s[58:59], v3, v152
	v_or_b32_e32 v3, 57, v0
	v_cmp_gt_i32_e64 s[60:61], v2, v152
	v_or_b32_e32 v2, 26, v0
	v_lshl_add_u64 v[160:161], s[6:7], 0, v[156:157]
	v_cmp_gt_i32_e64 s[6:7], v0, v152
	v_cmp_lt_i32_e64 s[10:11], v0, v152
	v_cmp_gt_i32_e64 s[62:63], v3, v152
	v_or_b32_e32 v3, 58, v0
	v_cmp_gt_i32_e64 s[64:65], v2, v152
	v_or_b32_e32 v2, 27, v0
	v_or_b32_e32 v0, 59, v0
	v_cmp_gt_i32_e64 s[70:71], v0, v152
	v_bitop3_b32 v0, v195, v193, 4 bitop3:0x36
	v_lshlrev_b32_e32 v201, 4, v0
	v_bitop3_b32 v0, v195, v194, 4 bitop3:0x36
	v_lshlrev_b32_e32 v202, 4, v0
	v_bitop3_b32 v0, v195, v193, 8 bitop3:0x36
	v_lshlrev_b32_e32 v203, 4, v0
	v_bitop3_b32 v0, v195, v194, 8 bitop3:0x36
	v_lshlrev_b32_e32 v204, 4, v0
	v_bitop3_b32 v0, v195, v193, 12 bitop3:0x36
	s_waitcnt vmcnt(0) lgkmcnt(0)
	s_barrier
	v_lshlrev_b32_e32 v205, 4, v0
	v_bitop3_b32 v0, v195, v194, 12 bitop3:0x36
	v_mov_b32_e32 v14, v1
	v_mov_b32_e32 v15, v1
	v_cmp_gt_i32_e64 s[66:67], v3, v152
	v_cmp_gt_i32_e64 s[68:69], v2, v152
	v_lshlrev_b32_e32 v206, 4, v0
	v_mov_b32_e32 v0, v1
	v_mov_b32_e32 v2, v1
	v_mov_b32_e32 v3, v1
	v_mov_b32_e32 v4, v1
	v_mov_b32_e32 v5, v1
	v_mov_b32_e32 v6, v1
	v_mov_b32_e32 v7, v1
	v_mov_b32_e32 v8, v1
	v_mov_b32_e32 v9, v1
	v_mov_b32_e32 v10, v1
	v_mov_b32_e32 v11, v1
	v_mov_b32_e32 v12, v1
	v_mov_b32_e32 v13, v1
	v_mov_b64_e32 v[30:31], v[14:15]
	v_mov_b64_e32 v[46:47], v[14:15]
	v_mov_b64_e32 v[62:63], v[14:15]
	v_mov_b64_e32 v[78:79], v[14:15]
	s_mov_b32 s82, s74
	s_mov_b64 s[74:75], s[90:91]
	v_lshlrev_b32_e32 v199, 4, v197
	v_lshlrev_b32_e32 v200, 4, v196
	s_mov_b32 s95, 0
	v_mov_b32_e32 v198, 0
	v_readlane_b32 s90, v248, 13
	v_mov_b64_e32 v[28:29], v[12:13]
	v_mov_b64_e32 v[26:27], v[10:11]
	v_mov_b64_e32 v[24:25], v[8:9]
	v_mov_b64_e32 v[22:23], v[6:7]
	v_mov_b64_e32 v[20:21], v[4:5]
	v_mov_b64_e32 v[18:19], v[2:3]
	v_mov_b64_e32 v[16:17], v[0:1]
	v_mov_b64_e32 v[44:45], v[12:13]
	v_mov_b64_e32 v[42:43], v[10:11]
	v_mov_b64_e32 v[40:41], v[8:9]
	v_mov_b64_e32 v[38:39], v[6:7]
	v_mov_b64_e32 v[36:37], v[4:5]
	v_mov_b64_e32 v[34:35], v[2:3]
	v_mov_b64_e32 v[32:33], v[0:1]
	v_mov_b64_e32 v[60:61], v[12:13]
	v_mov_b64_e32 v[58:59], v[10:11]
	v_mov_b64_e32 v[56:57], v[8:9]
	v_mov_b64_e32 v[54:55], v[6:7]
	v_mov_b64_e32 v[52:53], v[4:5]
	v_mov_b64_e32 v[50:51], v[2:3]
	v_mov_b64_e32 v[48:49], v[0:1]
	v_mov_b64_e32 v[76:77], v[12:13]
	v_mov_b64_e32 v[74:75], v[10:11]
	v_mov_b64_e32 v[72:73], v[8:9]
	v_mov_b64_e32 v[70:71], v[6:7]
	v_mov_b64_e32 v[68:69], v[4:5]
	v_mov_b64_e32 v[66:67], v[2:3]
	v_mov_b64_e32 v[64:65], v[0:1]
	v_mov_b32_e32 v224, 0
	v_mov_b32_e32 v221, 0
	v_mov_b32_e32 v217, 0
	v_mov_b32_e32 v213, 0
	v_mov_b32_e32 v209, 0
	v_mov_b32_e32 v110, 0
	v_mov_b32_e32 v106, 0
	v_mov_b32_e32 v102, 0
	v_mov_b32_e32 v97, 0
	v_mov_b32_e32 v93, 0
	v_mov_b32_e32 v89, 0
	v_mov_b32_e32 v85, 0
	v_mov_b32_e32 v81, 0
	v_mov_b32_e32 v13, 0
	v_mov_b32_e32 v9, 0
	v_mov_b32_e32 v5, 0
	v_mov_b32_e32 v223, 0
	v_mov_b32_e32 v219, 0
	v_mov_b32_e32 v215, 0
	v_mov_b32_e32 v211, 0
	v_mov_b32_e32 v207, 0
	v_mov_b32_e32 v108, 0
	v_mov_b32_e32 v104, 0
	v_mov_b32_e32 v99, 0
	v_mov_b32_e32 v95, 0
	v_mov_b32_e32 v91, 0
	v_mov_b32_e32 v87, 0
	v_mov_b32_e32 v83, 0
	v_mov_b32_e32 v15, 0
	v_mov_b32_e32 v11, 0
	v_mov_b32_e32 v7, 0
	v_mov_b32_e32 v3, 0
	v_mov_b32_e32 v222, 0
	v_mov_b32_e32 v218, 0
	v_mov_b32_e32 v214, 0
	v_mov_b32_e32 v210, 0
	v_mov_b32_e32 v111, 0
	v_mov_b32_e32 v107, 0
	v_mov_b32_e32 v103, 0
	v_mov_b32_e32 v98, 0
	v_mov_b32_e32 v94, 0
	v_mov_b32_e32 v90, 0
	v_mov_b32_e32 v86, 0
	v_mov_b32_e32 v82, 0
	v_mov_b32_e32 v14, 0
	v_mov_b32_e32 v10, 0
	v_mov_b32_e32 v6, 0
	v_mov_b32_e32 v2, 0
	v_mov_b32_e32 v220, 0
	v_mov_b32_e32 v216, 0
	v_mov_b32_e32 v212, 0
	v_mov_b32_e32 v208, 0
	v_mov_b32_e32 v109, 0
	v_mov_b32_e32 v105, 0
	v_mov_b32_e32 v100, 0
	v_mov_b32_e32 v96, 0
	v_mov_b32_e32 v92, 0
	v_mov_b32_e32 v88, 0
	v_mov_b32_e32 v84, 0
	v_mov_b32_e32 v80, 0
	v_mov_b32_e32 v12, 0
	v_mov_b32_e32 v8, 0
	v_mov_b32_e32 v4, 0
	v_mov_b32_e32 v0, 0
	s_add_i32 s72, s90, -4
	v_mov_b32_e32 v101, s72
	ds_read2_b32 v[220:221], v101 offset1:1
	s_waitcnt lgkmcnt(0)
	v_readfirstlane_b32 s92, v220
	s_cmp_lt_i32 s92, 32
	s_cselect_b64 vcc, -1, 0
	s_cmp_lt_u32 s92, 64
	s_cselect_b64 s[98:99], -1, 0
	s_cmpk_lt_u32 s92, 0x60
	s_cselect_b64 s[100:101], -1, 0
	v_cndmask_b32_e64 v223, v147, v146, s[100:101]
	v_cndmask_b32_e64 v223, v223, v145, s[98:99]
	v_cndmask_b32_e32 v223, v223, v144, vcc
	s_and_b32 s100, s92, 31
	v_bfe_u32 v223, v223, s100, 1
	v_cmp_ne_u32_e64 s[98:99], 0, v223
	s_branch .LBB0_744

.LBB0_743:
	v_readfirstlane_b32 s92, v221
	s_cmp_lt_i32 s92, 32
	s_cselect_b64 vcc, -1, 0
	s_cmp_lt_u32 s92, 64
	s_cselect_b64 s[98:99], -1, 0
	s_cmpk_lt_u32 s92, 0x60
	s_cselect_b64 s[100:101], -1, 0
	v_cndmask_b32_e64 v223, v147, v146, s[100:101]
	v_cndmask_b32_e64 v223, v223, v145, s[98:99]
	v_cndmask_b32_e32 v223, v223, v144, vcc
	s_and_b32 s100, s92, 31
	v_bfe_u32 v223, v223, s100, 1
	v_cmp_ne_u32_e64 s[98:99], 0, v223
	s_waitcnt vmcnt(0) lgkmcnt(0)
	v_mov_b32_e32 v220, v221
	v_mov_b32_e32 v221, v222
	s_barrier
	s_add_i32 s90, s90, 4
	s_cmp_lg_u32 s94, s95
	s_cbranch_scc0 .LBB0_751

.LBB0_746:
	s_mov_b64 s[72:73], s[98:99]
	s_cmp_lg_u64 s[98:99], 0
	s_cbranch_scc0 .LBB0_743
	s_lshl_b32 s76, s91, 14
	s_add_i32 s91, s76, 0
	s_cmp_eq_u32 s92, s33
	s_cbranch_scc0 .Lsel_fast2
	v_add_u32_e32 v0, s91, v184
	ds_read_b128 v[2:5], v0
	ds_read_b128 v[6:9], v0 offset:8192
	v_add_u32_e32 v0, s91, v185
	ds_read_b128 v[10:13], v0
	ds_read_b128 v[208:211], v0 offset:8192
	v_add_u32_e32 v0, s91, v186
	ds_read_b128 v[212:215], v0
	ds_read_b128 v[216:219], v0 offset:8192
	s_waitcnt lgkmcnt(0)
	v_mfma_f32_32x32x16_bf16 v[80:95], v[2:5], v[140:143], 0
	v_mfma_f32_32x32x16_bf16 v[96:111], v[6:9], v[140:143], 0
	v_add_u32_e32 v0, s91, v183
	ds_read_b128 v[2:5], v0
	ds_read_b128 v[6:9], v0 offset:8192
	v_mfma_f32_32x32x16_bf16 v[80:95], v[10:13], v[136:139], v[80:95]
	v_mfma_f32_32x32x16_bf16 v[96:111], v[208:211], v[136:139], v[96:111]
	v_add_u32_e32 v0, s91, v182
	ds_read_b128 v[10:13], v0
	ds_read_b128 v[208:211], v0 offset:8192
	v_mfma_f32_32x32x16_bf16 v[80:95], v[212:215], v[132:135], v[80:95]
	v_mfma_f32_32x32x16_bf16 v[96:111], v[216:219], v[132:135], v[96:111]
	v_add_u32_e32 v0, s91, v181
	ds_read_b128 v[212:215], v0
	ds_read_b128 v[216:219], v0 offset:8192
	s_waitcnt lgkmcnt(0)
	v_mfma_f32_32x32x16_bf16 v[80:95], v[2:5], v[128:131], v[80:95]
	v_mfma_f32_32x32x16_bf16 v[96:111], v[6:9], v[128:131], v[96:111]
	v_add_u32_e32 v0, s91, v180
	ds_read_b128 v[2:5], v0
	ds_read_b128 v[6:9], v0 offset:8192
	v_mfma_f32_32x32x16_bf16 v[80:95], v[10:13], v[124:127], v[80:95]
	v_mfma_f32_32x32x16_bf16 v[96:111], v[208:211], v[124:127], v[96:111]
	v_add_u32_e32 v0, s91, v179
	ds_read_b128 v[10:13], v0
	ds_read_b128 v[208:211], v0 offset:8192
	v_mfma_f32_32x32x16_bf16 v[80:95], v[212:215], v[120:123], v[80:95]
	v_mfma_f32_32x32x16_bf16 v[96:111], v[216:219], v[120:123], v[96:111]
	s_waitcnt lgkmcnt(0)
	v_mfma_f32_32x32x16_bf16 v[80:95], v[2:5], v[116:119], v[80:95]
	v_mfma_f32_32x32x16_bf16 v[96:111], v[6:9], v[116:119], v[96:111]
	v_mfma_f32_32x32x16_bf16 v[80:95], v[10:13], v[112:115], v[80:95]
	v_mfma_f32_32x32x16_bf16 v[96:111], v[208:211], v[112:115], v[96:111]
	s_nop 10
	s_cmp_eq_u32 s92, s33
	s_cbranch_scc0 .Lsel_fast
	v_exp_f32_e32 v6, v80
	v_exp_f32_e32 v0, v96
	v_exp_f32_e32 v9, v81
	v_exp_f32_e32 v3, v97
	v_exp_f32_e32 v8, v82
	v_exp_f32_e32 v2, v98
	v_exp_f32_e32 v11, v83
	v_exp_f32_e32 v5, v99
	v_exp_f32_e32 v10, v84
	v_exp_f32_e32 v4, v100
	v_exp_f32_e32 v13, v85
	v_exp_f32_e32 v7, v101
	v_exp_f32_e32 v96, v86
	v_exp_f32_e32 v82, v102
	v_exp_f32_e32 v97, v87
	v_exp_f32_e32 v83, v103
	v_exp_f32_e32 v88, v88
	v_exp_f32_e32 v14, v104
	v_exp_f32_e32 v89, v89
	v_exp_f32_e32 v15, v105
	v_exp_f32_e32 v90, v90
	v_exp_f32_e32 v80, v106
	v_exp_f32_e32 v91, v91
	v_exp_f32_e32 v81, v107
	v_exp_f32_e32 v92, v92
	v_exp_f32_e32 v84, v108
	v_exp_f32_e32 v93, v93
	v_exp_f32_e32 v85, v109
	v_exp_f32_e32 v94, v94
	v_exp_f32_e32 v86, v110
	v_exp_f32_e32 v95, v95
	v_exp_f32_e32 v87, v111
	s_cmp_eq_u32 s92, s33
	s_mov_b64 s[76:77], -1
	s_cbranch_scc1 .LBB0_749
	s_mov_b64 s[76:77], 0
